# compress item: also preload the 8 Z1-row A fragments up front (A+B preload)
# baseline (speedup 1.0000x reference)
; DI unsigned cvtpk(float lo, float hi) { return pg8::cvt_pk_bf16(lo, hi); }
; DI void compress_item(const Args& a, int l, int item, unsigned char* lds, int tid) {
;     ...
;     const int tix = item % 17, r3 = item / 17, j = r3 & 1, g = (r3 >> 1) & 1, b = r3 >> 2;
;     const float* pe = a.in[5] + ((size_t)l * 2 + j) * 2048; const float* w2 = a.in[7] + ((size_t)l * 2 + j) * 64 * 64; const float* g1 = a.in[4] + (size_t)l * 4 * 64 + 64;
;     const int r = lane & 15, kq = lane >> 4, n = 15 * tix + r;
;     const bf16_t* arow = Z1 + ((size_t)b * SEQ + 16 * n) * ZP + C_KV + j * 128 + g * 64;
;     const bf16_t* wrow = W1T + (size_t)j * 64 * 2048 + (size_t)r * 2048;
;     float* part = (float*)lds; float* hs = (float*)(lds + 32768);
;     pg8::f32x4 acc[4];
; #pragma unroll
;     for (int ct = 0; ct < 4; ++ct) acc[ct] = (pg8::f32x4){0.f, 0.f, 0.f, 0.f};
; #pragma unroll
;     for (int ks = 0; ks < 8; ++ks) { const int kk = wave * 256 + ks * 32 + kq * 8, li = kk >> 6, d0 = kk & 63; bf16x8 af;
;         if (r < 15) af = *(const bf16x8*)(arow + (size_t)li * ZP + d0);
;         else { const f32x4 p0 = *(const f32x4*)(pe + kk), p1 = *(const f32x4*)(pe + kk + 4); u32x4 w; w.x = cvtpk(p0[0], p0[1]); w.y = cvtpk(p0[2], p0[3]); w.z = cvtpk(p1[0], p1[1]); w.w = cvtpk(p1[2], p1[3]); af = __builtin_bit_cast(bf16x8, w); }
; #pragma unroll
;         for (int ct = 0; ct < 4; ++ct) { const bf16x8 bfr = *(const bf16x8*)(wrow + (size_t)ct * 16 * 2048 + kk); acc[ct] = __builtin_amdgcn_mfma_f32_16x16x32_bf16(af, bfr, acc[ct], 0, 0, 0); } }
.LBB0_302:
	v_mov_b32_e32 v146, v225
	s_cmpk_gt_i32 s25, 0xff
	s_cbranch_scc0 .LBB0_349
	s_cmpk_gt_u32 s25, 0x2ff
	s_cbranch_scc0 .LBB0_350
	s_cmpk_gt_u32 s25, 0x4ff
	s_cbranch_scc0 .LBB0_351
	s_add_i32 s0, s25, 0xfb00
	s_and_b32 s1, s0, 0xffff
	s_mul_i32 s1, s1, 0xf0f1
	s_lshr_b32 s6, s1, 20
	s_mul_i32 s6, s6, 17
	s_sub_i32 s55, s0, s6
	s_mul_i32 s8, s55, 15
	v_and_b32_e32 v32, 15, v146
	s_and_b32 s54, s8, 0xffff
	v_readlane_b32 s10, v254, 3
	s_bfe_u32 s9, s1, 0x10014
	s_lshr_b32 s53, s1, 22
	v_add_lshl_u32 v0, v32, s54, 4
	v_readlane_b32 s11, v254, 4
	v_readfirstlane_b32 s59, v146
	s_bfe_u32 s52, s1, 0x10015
	s_or_b32 s0, s12, s9
	s_mov_b32 s1, s13
	v_lshl_add_u32 v2, s53, 12, v0
	v_mov_b64_e32 v[0:1], s[10:11]
	v_readlane_b32 s36, v253, 35
	s_lshl_b64 s[6:7], s[0:1], 13
	v_mad_u64_u32 v[0:1], s[10:11], v2, s3, v[0:1]
	s_ashr_i32 s8, s59, 6
	v_readlane_b32 s46, v253, 45
	v_readlane_b32 s47, v253, 46
	s_add_u32 s10, s46, s6
	s_addc_u32 s11, s47, s7
	v_bfe_u32 v33, v146, 4, 2
	s_lshl_b32 s80, s9, 8
	v_lshl_add_u64 v[0:1], v[0:1], 0, s[80:81]
	s_lshl_b32 s80, s52, 7
	s_lshl_b32 s34, s8, 8
	v_lshlrev_b32_e32 v26, 3, v33
	v_lshl_add_u64 v[0:1], v[0:1], 0, s[80:81]
	s_mov_b64 s[6:7], 0x7101000
	v_or_b32_e32 v20, s34, v26
	v_readlane_b32 s37, v253, 36
	v_lshl_add_u64 v[28:29], v[0:1], 0, s[6:7]
	v_cmp_ne_u32_e64 s[6:7], 15, v32
	v_lshlrev_b32_e32 v30, 1, v26
	v_ashrrev_i32_e32 v21, 31, v20
	v_readlane_b32 s38, v253, 37
	v_readlane_b32 s39, v253, 38
	v_readlane_b32 s40, v253, 39
	v_readlane_b32 s41, v253, 40
	v_readlane_b32 s42, v253, 41
	v_readlane_b32 s43, v253, 42
	v_readlane_b32 s44, v253, 43
	v_readlane_b32 s45, v253, 44
	v_readlane_b32 s48, v253, 47
	v_readlane_b32 s49, v253, 48
	v_readlane_b32 s50, v253, 49
	v_readlane_b32 s51, v253, 50
	s_and_saveexec_b64 s[36:37], s[6:7]
	s_xor_b64 s[36:37], exec, s[36:37]
	s_cbranch_execz .LBB0_307
	s_lshl_b32 s35, s8, 2
	v_mov_b32_e32 v0, 0x2230
	v_mad_i64_i32 v[0:1], s[56:57], s35, v0, v[28:29]
	v_mov_b32_e32 v31, v161
	v_lshl_add_u64 v[0:1], v[0:1], 0, v[30:31]
	v_mov_b64_e32 v[206:207], v[0:1]
	s_movk_i32 s100, 0x2230
	s_mov_b32 s101, 0
	v_lshl_add_u64 v[212:213], v[0:1], 0, s[100:101]
	s_movk_i32 s100, 0x4460
	v_lshl_add_u64 v[226:227], v[0:1], 0, s[100:101]
	s_movk_i32 s100, 0x6690
	v_lshl_add_u64 v[144:145], v[0:1], 0, s[100:101]
	global_load_dwordx4 v[208:211], v[206:207], off
	global_load_dwordx4 v[220:223], v[206:207], off offset:64
	global_load_dwordx4 v[228:231], v[212:213], off
	global_load_dwordx4 v[232:235], v[212:213], off offset:64
	global_load_dwordx4 v[236:239], v[226:227], off
	global_load_dwordx4 v[240:243], v[226:227], off offset:64
	global_load_dwordx4 v[244:247], v[144:145], off
	global_load_dwordx4 v[248:251], v[144:145], off offset:64
.LBB0_307:
	s_andn2_saveexec_b64 s[36:37], s[36:37]
	s_cbranch_execz .LBB0_309
	v_lshl_add_u64 v[4:5], v[20:21], 2, s[10:11]
	global_load_dwordx4 v[0:3], v[4:5], off
	s_nop 0
	global_load_dwordx4 v[4:7], v[4:5], off offset:16
	s_waitcnt vmcnt(0)
	v_cvt_pk_bf16_f32 v208, v0, v1
	v_cvt_pk_bf16_f32 v209, v2, v3
	s_waitcnt vmcnt(0)
	v_cvt_pk_bf16_f32 v210, v4, v5
	v_cvt_pk_bf16_f32 v211, v6, v7
.LBB0_309:
	s_or_b64 exec, exec, s[36:37]
	s_lshl_b32 s35, s9, 18
	s_add_u32 s36, s84, s35
	s_addc_u32 s37, s90, 0
	v_lshlrev_b32_e32 v160, 12, v32
	v_lshl_add_u64 v[24:25], s[36:37], 0, v[160:161]
	v_lshl_add_u64 v[16:17], v[20:21], 1, v[24:25]
	s_mov_b32 s100, 0x10000
	s_mov_b32 s101, 0
	v_lshl_add_u64 v[200:201], v[16:17], 0, s[100:101]
	s_mov_b32 s100, 0x20000
	v_lshl_add_u64 v[202:203], v[16:17], 0, s[100:101]
	s_mov_b32 s100, 0x30000
	v_lshl_add_u64 v[204:205], v[16:17], 0, s[100:101]
	global_load_dwordx4 v[56:59], v[16:17], off
	global_load_dwordx4 v[60:63], v[200:201], off
	global_load_dwordx4 v[64:67], v[202:203], off
	global_load_dwordx4 v[68:71], v[204:205], off
	global_load_dwordx4 v[72:75], v[16:17], off offset:64
	global_load_dwordx4 v[76:79], v[200:201], off offset:64
	global_load_dwordx4 v[80:83], v[202:203], off offset:64
	global_load_dwordx4 v[84:87], v[204:205], off offset:64
	global_load_dwordx4 v[88:91], v[16:17], off offset:128
	global_load_dwordx4 v[92:95], v[200:201], off offset:128
	global_load_dwordx4 v[96:99], v[202:203], off offset:128
	global_load_dwordx4 v[100:103], v[204:205], off offset:128
	global_load_dwordx4 v[104:107], v[16:17], off offset:192
	global_load_dwordx4 v[108:111], v[200:201], off offset:192
	global_load_dwordx4 v[112:115], v[202:203], off offset:192
	global_load_dwordx4 v[116:119], v[204:205], off offset:192
	global_load_dwordx4 v[120:123], v[16:17], off offset:256
	global_load_dwordx4 v[124:127], v[200:201], off offset:256
	global_load_dwordx4 v[128:131], v[202:203], off offset:256
	global_load_dwordx4 v[132:135], v[204:205], off offset:256
	global_load_dwordx4 v[136:139], v[16:17], off offset:320
	global_load_dwordx4 v[140:143], v[200:201], off offset:320
	global_load_dwordx4 v[148:151], v[202:203], off offset:320
	global_load_dwordx4 v[152:155], v[204:205], off offset:320
	global_load_dwordx4 v[156:159], v[16:17], off offset:384
	global_load_dwordx4 v[168:171], v[200:201], off offset:384
	global_load_dwordx4 v[172:175], v[202:203], off offset:384
	global_load_dwordx4 v[176:179], v[204:205], off offset:384
	global_load_dwordx4 v[180:183], v[16:17], off offset:448
	global_load_dwordx4 v[184:187], v[200:201], off offset:448
	global_load_dwordx4 v[188:191], v[202:203], off offset:448
	global_load_dwordx4 v[192:195], v[204:205], off offset:448
	s_mov_b32 s35, 0x10000
	v_add_co_u32_e32 v8, vcc, s35, v16
	s_nop 0
	v_addc_co_u32_e32 v9, vcc, 0, v17, vcc
	v_add_co_u32_e32 v12, vcc, 0x20000, v16
	s_nop 0
	v_addc_co_u32_e32 v13, vcc, 0, v17, vcc
	v_add_co_u32_e32 v16, vcc, 0x30000, v16
	s_nop 0
	v_addc_co_u32_e32 v17, vcc, 0, v17, vcc
	v_or_b32_e32 v22, 32, v20
	v_ashrrev_i32_e32 v23, 31, v22
	s_waitcnt vmcnt(0)
	v_mfma_f32_16x16x32_bf16 v[4:7], v[208:211], v[56:59], 0
	v_mfma_f32_16x16x32_bf16 v[8:11], v[208:211], v[60:63], 0
	v_mfma_f32_16x16x32_bf16 v[12:15], v[208:211], v[64:67], 0
	v_mfma_f32_16x16x32_bf16 v[0:3], v[208:211], v[68:71], 0
	s_and_saveexec_b64 s[36:37], s[6:7]
	s_xor_b64 s[36:37], exec, s[36:37]
	s_cbranch_execz .LBB0_311
	v_and_b32_e32 v18, 56, v22
	s_lshl_b32 s35, s8, 2
	v_mov_b32_e32 v16, 0x2230
	v_mad_i64_i32 v[16:17], s[56:57], s35, v16, v[28:29]
	v_lshlrev_b32_e32 v160, 1, v18
	v_lshl_add_u64 v[16:17], v[16:17], 0, v[160:161]
; DI unsigned cvtpk(float lo, float hi) { return pg8::cvt_pk_bf16(lo, hi); }
; DI void compress_item(const Args& a, int l, int item, unsigned char* lds, int tid) {
;     ...
;     for (int ks = 0; ks < 8; ++ks) { const int kk = wave * 256 + ks * 32 + kq * 8, li = kk >> 6, d0 = kk & 63; bf16x8 af;
;         if (r < 15) af = *(const bf16x8*)(arow + (size_t)li * ZP + d0);
;         else { const f32x4 p0 = *(const f32x4*)(pe + kk), p1 = *(const f32x4*)(pe + kk + 4); u32x4 w; w.x = cvtpk(p0[0], p0[1]); w.y = cvtpk(p0[2], p0[3]); w.z = cvtpk(p1[0], p1[1]); w.w = cvtpk(p1[2], p1[3]); af = __builtin_bit_cast(bf16x8, w); }
; #pragma unroll
;         for (int ct = 0; ct < 4; ++ct) { const bf16x8 bfr = *(const bf16x8*)(wrow + (size_t)ct * 16 * 2048 + kk); acc[ct] = __builtin_amdgcn_mfma_f32_16x16x32_bf16(af, bfr, acc[ct], 0, 0, 0); } }
.LBB0_311:
	s_andn2_saveexec_b64 s[36:37], s[36:37]
	s_cbranch_execz .LBB0_313
	v_lshl_add_u64 v[20:21], v[20:21], 2, s[10:11]
	global_load_dwordx4 v[16:19], v[20:21], off offset:128
	global_load_dwordx4 v[34:37], v[20:21], off offset:144
	s_waitcnt vmcnt(1)
	v_cvt_pk_bf16_f32 v220, v16, v17
	v_cvt_pk_bf16_f32 v221, v18, v19
	s_waitcnt vmcnt(0)
	v_cvt_pk_bf16_f32 v222, v34, v35
	v_cvt_pk_bf16_f32 v223, v36, v37
.LBB0_313:
	s_or_b64 exec, exec, s[36:37]
	v_lshl_add_u64 v[34:35], v[22:23], 1, v[24:25]
	s_or_b32 s35, s34, 64
	s_waitcnt vmcnt(0)
	v_mfma_f32_16x16x32_bf16 v[4:7], v[220:223], v[72:75], v[4:7]
	v_add_co_u32_e32 v20, vcc, 0x10000, v34
	s_nop 1
	v_addc_co_u32_e32 v21, vcc, 0, v35, vcc
	v_mfma_f32_16x16x32_bf16 v[8:11], v[220:223], v[76:79], v[8:11]
	v_add_co_u32_e32 v20, vcc, 0x20000, v34
	s_nop 1
	v_addc_co_u32_e32 v21, vcc, 0, v35, vcc
	v_mfma_f32_16x16x32_bf16 v[12:15], v[220:223], v[80:83], v[12:15]
	v_add_co_u32_e32 v20, vcc, 0x30000, v34
	s_nop 1
	v_addc_co_u32_e32 v21, vcc, 0, v35, vcc
	v_mfma_f32_16x16x32_bf16 v[16:19], v[220:223], v[84:87], v[0:3]
	s_nop 2
	v_or_b32_e32 v0, s35, v26
	v_ashrrev_i32_e32 v1, 31, v0
	s_and_saveexec_b64 s[36:37], s[6:7]
	s_xor_b64 s[36:37], exec, s[36:37]
	s_cbranch_execz .LBB0_315
	s_ashr_i32 s35, s35, 6
	v_mov_b32_e32 v2, 0x2230
	v_mad_i64_i32 v[2:3], s[56:57], s35, v2, v[28:29]
	v_mov_b32_e32 v31, v161
	v_lshl_add_u64 v[2:3], v[2:3], 0, v[30:31]
.LBB0_315:
	s_andn2_saveexec_b64 s[36:37], s[36:37]
	s_cbranch_execz .LBB0_317
	v_mov_b32_e32 v27, v161
	s_ashr_i32 s35, s34, 31
	v_lshl_add_u64 v[2:3], s[34:35], 0, v[26:27]
	v_lshl_add_u64 v[2:3], v[2:3], 2, s[10:11]
	global_load_dwordx4 v[20:23], v[2:3], off offset:256
	global_load_dwordx4 v[34:37], v[2:3], off offset:272
	s_waitcnt vmcnt(1)
	v_cvt_pk_bf16_f32 v228, v20, v21
	v_cvt_pk_bf16_f32 v229, v22, v23
	s_waitcnt vmcnt(0)
	v_cvt_pk_bf16_f32 v230, v34, v35
	v_cvt_pk_bf16_f32 v231, v36, v37
.LBB0_317:
	s_or_b64 exec, exec, s[36:37]
	v_lshl_add_u64 v[34:35], v[0:1], 1, v[24:25]
	s_or_b32 s35, s34, 0x60
	s_waitcnt vmcnt(0)
	v_mfma_f32_16x16x32_bf16 v[0:3], v[228:231], v[88:91], v[4:7]
	s_nop 2
	v_add_co_u32_e32 v4, vcc, 0x10000, v34
	s_nop 1
	v_addc_co_u32_e32 v5, vcc, 0, v35, vcc
	v_mfma_f32_16x16x32_bf16 v[4:7], v[228:231], v[92:95], v[8:11]
	s_nop 2
	v_add_co_u32_e32 v8, vcc, 0x20000, v34
	s_nop 1
	v_addc_co_u32_e32 v9, vcc, 0, v35, vcc
	v_mfma_f32_16x16x32_bf16 v[8:11], v[228:231], v[96:99], v[12:15]
	s_nop 2
	v_add_co_u32_e32 v12, vcc, 0x30000, v34
	s_nop 1
	v_addc_co_u32_e32 v13, vcc, 0, v35, vcc
	v_mfma_f32_16x16x32_bf16 v[12:15], v[228:231], v[100:103], v[16:19]
	v_or_b32_e32 v20, s35, v26
	v_ashrrev_i32_e32 v21, 31, v20
	s_and_saveexec_b64 s[36:37], s[6:7]
	s_xor_b64 s[36:37], exec, s[36:37]
	s_cbranch_execz .LBB0_319
	v_and_b32_e32 v18, 56, v20
	s_ashr_i32 s35, s35, 6
	v_mov_b32_e32 v16, 0x2230
	v_mad_i64_i32 v[16:17], s[56:57], s35, v16, v[28:29]
	v_lshlrev_b32_e32 v160, 1, v18
	v_lshl_add_u64 v[16:17], v[16:17], 0, v[160:161]
.LBB0_319:
	s_andn2_saveexec_b64 s[36:37], s[36:37]
	s_cbranch_execz .LBB0_321
	v_mov_b32_e32 v27, v161
	s_ashr_i32 s35, s34, 31
	s_waitcnt vmcnt(0)
	v_lshl_add_u64 v[16:17], s[34:35], 0, v[26:27]
	v_lshl_add_u64 v[22:23], v[16:17], 2, s[10:11]
	global_load_dwordx4 v[16:19], v[22:23], off offset:384
	global_load_dwordx4 v[34:37], v[22:23], off offset:400
	s_waitcnt vmcnt(1)
	v_cvt_pk_bf16_f32 v232, v16, v17
	v_cvt_pk_bf16_f32 v233, v18, v19
	s_waitcnt vmcnt(0)
	v_cvt_pk_bf16_f32 v234, v34, v35
	v_cvt_pk_bf16_f32 v235, v36, v37
.LBB0_321:
	s_or_b64 exec, exec, s[36:37]
	v_lshl_add_u64 v[34:35], v[20:21], 1, v[24:25]
	s_or_b32 s35, s34, 0x80
	s_waitcnt vmcnt(0)
	v_mfma_f32_16x16x32_bf16 v[0:3], v[232:235], v[104:107], v[0:3]
	v_add_co_u32_e32 v20, vcc, 0x10000, v34
	s_nop 1
	v_addc_co_u32_e32 v21, vcc, 0, v35, vcc
	v_mfma_f32_16x16x32_bf16 v[4:7], v[232:235], v[108:111], v[4:7]
	v_add_co_u32_e32 v20, vcc, 0x20000, v34
	s_nop 1
	v_addc_co_u32_e32 v21, vcc, 0, v35, vcc
	v_mfma_f32_16x16x32_bf16 v[8:11], v[232:235], v[112:115], v[8:11]
	v_add_co_u32_e32 v20, vcc, 0x30000, v34
	s_nop 1
	v_addc_co_u32_e32 v21, vcc, 0, v35, vcc
	v_mfma_f32_16x16x32_bf16 v[12:15], v[232:235], v[116:119], v[12:15]
	v_or_b32_e32 v20, s35, v26
	v_ashrrev_i32_e32 v21, 31, v20
	s_and_saveexec_b64 s[36:37], s[6:7]
	s_xor_b64 s[36:37], exec, s[36:37]
	s_cbranch_execz .LBB0_323
	s_ashr_i32 s35, s35, 6
	v_mov_b32_e32 v16, 0x2230
	v_mad_i64_i32 v[16:17], s[56:57], s35, v16, v[28:29]
	v_mov_b32_e32 v31, v161
	v_lshl_add_u64 v[16:17], v[16:17], 0, v[30:31]
.LBB0_323:
	s_andn2_saveexec_b64 s[36:37], s[36:37]
	s_cbranch_execz .LBB0_325
	v_mov_b32_e32 v27, v161
	s_ashr_i32 s35, s34, 31
	s_waitcnt vmcnt(0)
	v_lshl_add_u64 v[16:17], s[34:35], 0, v[26:27]
	v_lshl_add_u64 v[22:23], v[16:17], 2, s[10:11]
	global_load_dwordx4 v[16:19], v[22:23], off offset:512
	global_load_dwordx4 v[34:37], v[22:23], off offset:528
	s_waitcnt vmcnt(1)
	v_cvt_pk_bf16_f32 v236, v16, v17
	v_cvt_pk_bf16_f32 v237, v18, v19
	s_waitcnt vmcnt(0)
	v_cvt_pk_bf16_f32 v238, v34, v35
	v_cvt_pk_bf16_f32 v239, v36, v37
.LBB0_325:
	s_or_b64 exec, exec, s[36:37]
	v_lshl_add_u64 v[34:35], v[20:21], 1, v[24:25]
	s_or_b32 s35, s34, 0xa0
	s_waitcnt vmcnt(0)
	v_mfma_f32_16x16x32_bf16 v[0:3], v[236:239], v[120:123], v[0:3]
	v_add_co_u32_e32 v20, vcc, 0x10000, v34
	s_nop 1
	v_addc_co_u32_e32 v21, vcc, 0, v35, vcc
	v_mfma_f32_16x16x32_bf16 v[4:7], v[236:239], v[124:127], v[4:7]
	v_add_co_u32_e32 v20, vcc, 0x20000, v34
	s_nop 1
	v_addc_co_u32_e32 v21, vcc, 0, v35, vcc
	v_mfma_f32_16x16x32_bf16 v[8:11], v[236:239], v[128:131], v[8:11]
	v_add_co_u32_e32 v20, vcc, 0x30000, v34
	s_nop 1
	v_addc_co_u32_e32 v21, vcc, 0, v35, vcc
	v_mfma_f32_16x16x32_bf16 v[12:15], v[236:239], v[132:135], v[12:15]
	v_or_b32_e32 v16, s35, v26
	v_ashrrev_i32_e32 v17, 31, v16
	s_and_saveexec_b64 s[36:37], s[6:7]
	s_xor_b64 s[36:37], exec, s[36:37]
	s_cbranch_execz .LBB0_327
	v_and_b32_e32 v20, 56, v16
	s_ashr_i32 s35, s35, 6
	v_mov_b32_e32 v18, 0x2230
	v_mad_i64_i32 v[18:19], s[56:57], s35, v18, v[28:29]
	v_lshlrev_b32_e32 v160, 1, v20
	v_lshl_add_u64 v[18:19], v[18:19], 0, v[160:161]
; DI unsigned cvtpk(float lo, float hi) { return pg8::cvt_pk_bf16(lo, hi); }
; DI void compress_item(const Args& a, int l, int item, unsigned char* lds, int tid) {
;     ...
;     for (int ks = 0; ks < 8; ++ks) { const int kk = wave * 256 + ks * 32 + kq * 8, li = kk >> 6, d0 = kk & 63; bf16x8 af;
;         if (r < 15) af = *(const bf16x8*)(arow + (size_t)li * ZP + d0);
;         else { const f32x4 p0 = *(const f32x4*)(pe + kk), p1 = *(const f32x4*)(pe + kk + 4); u32x4 w; w.x = cvtpk(p0[0], p0[1]); w.y = cvtpk(p0[2], p0[3]); w.z = cvtpk(p1[0], p1[1]); w.w = cvtpk(p1[2], p1[3]); af = __builtin_bit_cast(bf16x8, w); }
; #pragma unroll
;         for (int ct = 0; ct < 4; ++ct) { const bf16x8 bfr = *(const bf16x8*)(wrow + (size_t)ct * 16 * 2048 + kk); acc[ct] = __builtin_amdgcn_mfma_f32_16x16x32_bf16(af, bfr, acc[ct], 0, 0, 0); } }
; #pragma unroll
;     for (int ct = 0; ct < 4; ++ct)
; #pragma unroll
;         for (int i = 0; i < 4; ++i) part[wave * 1024 + (4 * kq + i) * 64 + ct * 16 + r] = acc[ct][i];
;     __syncthreads();
.LBB0_327:
	s_andn2_saveexec_b64 s[36:37], s[36:37]
	s_cbranch_execz .LBB0_329
	v_mov_b32_e32 v27, v161
	s_ashr_i32 s35, s34, 31
	v_lshl_add_u64 v[18:19], s[34:35], 0, v[26:27]
	v_lshl_add_u64 v[18:19], v[18:19], 2, s[10:11]
	global_load_dwordx4 v[20:23], v[18:19], off offset:640
	global_load_dwordx4 v[34:37], v[18:19], off offset:656
	s_waitcnt vmcnt(1)
	v_cvt_pk_bf16_f32 v240, v20, v21
	v_cvt_pk_bf16_f32 v241, v22, v23
	s_waitcnt vmcnt(0)
	v_cvt_pk_bf16_f32 v242, v34, v35
	v_cvt_pk_bf16_f32 v243, v36, v37
.LBB0_329:
	s_or_b64 exec, exec, s[36:37]
	v_lshl_add_u64 v[34:35], v[16:17], 1, v[24:25]
	s_or_b32 s35, s34, 0xc0
	s_waitcnt vmcnt(0)
	v_mfma_f32_16x16x32_bf16 v[0:3], v[240:243], v[136:139], v[0:3]
	v_add_co_u32_e32 v16, vcc, 0x10000, v34
	s_nop 1
	v_addc_co_u32_e32 v17, vcc, 0, v35, vcc
	v_mfma_f32_16x16x32_bf16 v[4:7], v[240:243], v[140:143], v[4:7]
	v_add_co_u32_e32 v16, vcc, 0x20000, v34
	s_nop 1
	v_addc_co_u32_e32 v17, vcc, 0, v35, vcc
	v_mfma_f32_16x16x32_bf16 v[16:19], v[240:243], v[148:151], v[8:11]
	s_nop 2
	v_add_co_u32_e32 v8, vcc, 0x30000, v34
	s_nop 1
	v_addc_co_u32_e32 v9, vcc, 0, v35, vcc
	v_mfma_f32_16x16x32_bf16 v[12:15], v[240:243], v[152:155], v[12:15]
	v_or_b32_e32 v8, s35, v26
	v_ashrrev_i32_e32 v9, 31, v8
	s_and_saveexec_b64 s[36:37], s[6:7]
	s_xor_b64 s[36:37], exec, s[36:37]
	s_cbranch_execz .LBB0_331
	s_ashr_i32 s35, s35, 6
	v_mov_b32_e32 v10, 0x2230
	v_mad_i64_i32 v[10:11], s[56:57], s35, v10, v[28:29]
	v_mov_b32_e32 v31, v161
	v_lshl_add_u64 v[10:11], v[10:11], 0, v[30:31]
.LBB0_331:
	s_andn2_saveexec_b64 s[36:37], s[36:37]
	s_cbranch_execz .LBB0_333
	v_mov_b32_e32 v27, v161
	s_ashr_i32 s35, s34, 31
	v_lshl_add_u64 v[10:11], s[34:35], 0, v[26:27]
	v_lshl_add_u64 v[10:11], v[10:11], 2, s[10:11]
	global_load_dwordx4 v[20:23], v[10:11], off offset:768
	global_load_dwordx4 v[34:37], v[10:11], off offset:784
	s_waitcnt vmcnt(1)
	v_cvt_pk_bf16_f32 v244, v20, v21
	v_cvt_pk_bf16_f32 v245, v22, v23
	s_waitcnt vmcnt(0)
	v_cvt_pk_bf16_f32 v246, v34, v35
	v_cvt_pk_bf16_f32 v247, v36, v37
.LBB0_333:
	s_or_b64 exec, exec, s[36:37]
	v_lshl_add_u64 v[30:31], v[8:9], 1, v[24:25]
	s_or_b32 s35, s34, 0xe0
	s_waitcnt vmcnt(0)
	v_mfma_f32_16x16x32_bf16 v[8:11], v[244:247], v[156:159], v[0:3]
	s_nop 2
	v_add_co_u32_e32 v0, vcc, 0x10000, v30
	s_nop 1
	v_addc_co_u32_e32 v1, vcc, 0, v31, vcc
	v_mfma_f32_16x16x32_bf16 v[0:3], v[244:247], v[168:171], v[4:7]
	s_nop 2
	v_add_co_u32_e32 v4, vcc, 0x20000, v30
	s_nop 1
	v_addc_co_u32_e32 v5, vcc, 0, v31, vcc
	v_mfma_f32_16x16x32_bf16 v[4:7], v[244:247], v[172:175], v[16:19]
	s_nop 2
	v_add_co_u32_e32 v16, vcc, 0x30000, v30
	s_nop 1
	v_addc_co_u32_e32 v17, vcc, 0, v31, vcc
	v_mfma_f32_16x16x32_bf16 v[12:15], v[244:247], v[176:179], v[12:15]
	v_or_b32_e32 v20, s35, v26
	v_ashrrev_i32_e32 v21, 31, v20
	s_and_saveexec_b64 s[36:37], s[6:7]
	s_xor_b64 s[6:7], exec, s[36:37]
	s_cbranch_execz .LBB0_335
	v_and_b32_e32 v18, 56, v20
	s_ashr_i32 s35, s35, 6
	v_mov_b32_e32 v16, 0x2230
	v_mad_i64_i32 v[16:17], s[36:37], s35, v16, v[28:29]
	v_lshlrev_b32_e32 v160, 1, v18
	v_lshl_add_u64 v[16:17], v[16:17], 0, v[160:161]
.LBB0_335:
	s_andn2_saveexec_b64 s[6:7], s[6:7]
	s_cbranch_execz .LBB0_337
	v_mov_b32_e32 v27, v161
	s_ashr_i32 s35, s34, 31
	s_waitcnt vmcnt(0)
	v_lshl_add_u64 v[16:17], s[34:35], 0, v[26:27]
	v_lshl_add_u64 v[22:23], v[16:17], 2, s[10:11]
	global_load_dwordx4 v[16:19], v[22:23], off offset:896
	global_load_dwordx4 v[26:29], v[22:23], off offset:912
	s_waitcnt vmcnt(1)
	v_cvt_pk_bf16_f32 v248, v16, v17
	v_cvt_pk_bf16_f32 v249, v18, v19
	s_waitcnt vmcnt(0)
	v_cvt_pk_bf16_f32 v250, v26, v27
	v_cvt_pk_bf16_f32 v251, v28, v29
.LBB0_337:
	s_or_b64 exec, exec, s[6:7]
	v_lshl_add_u64 v[20:21], v[20:21], 1, v[24:25]
	s_mov_b32 s6, 0x10000
	v_readlane_b32 s36, v253, 35
	s_lshl_b64 s[0:1], s[0:1], 14
	v_readlane_b32 s50, v253, 49
	v_readlane_b32 s51, v253, 50
	s_add_u32 s0, s50, s0
	s_addc_u32 s1, s51, s1
	v_and_b32_e32 v22, 63, v146
	v_lshlrev_b32_e32 v160, 2, v22
	v_readlane_b32 s37, v253, 36
	v_readlane_b32 s38, v253, 37
	v_readlane_b32 s39, v253, 38
	v_readlane_b32 s40, v253, 39
	v_readlane_b32 s41, v253, 40
	v_readlane_b32 s42, v253, 41
	v_readlane_b32 s43, v253, 42
	v_readlane_b32 s44, v253, 43
	v_readlane_b32 s45, v253, 44
	v_readlane_b32 s46, v253, 45
	v_readlane_b32 s47, v253, 46
	v_readlane_b32 s48, v253, 47
	v_readlane_b32 s49, v253, 48
	s_waitcnt vmcnt(0)
	v_mfma_f32_16x16x32_bf16 v[8:11], v[248:251], v[180:183], v[8:11]
	v_add_co_u32_e32 v24, vcc, s6, v20
	s_mov_b32 s6, 0x20000
	s_nop 0
	v_addc_co_u32_e32 v25, vcc, 0, v21, vcc
	v_mfma_f32_16x16x32_bf16 v[0:3], v[248:251], v[184:187], v[0:3]
	v_add_co_u32_e32 v24, vcc, s6, v20
	s_mov_b32 s6, 0x30000
	s_nop 0
	v_addc_co_u32_e32 v25, vcc, 0, v21, vcc
	v_add_co_u32_e32 v20, vcc, s6, v20
	s_lshl_b32 s6, s8, 12
	s_nop 0
	v_addc_co_u32_e32 v21, vcc, 0, v21, vcc
	s_add_i32 s6, s6, 0
	v_mfma_f32_16x16x32_bf16 v[4:7], v[248:251], v[188:191], v[4:7]
	v_mfma_f32_16x16x32_bf16 v[12:15], v[248:251], v[192:195], v[12:15]
	v_lshlrev_b32_e32 v16, 10, v33
	v_lshlrev_b32_e32 v17, 2, v32
	v_add3_u32 v16, s6, v16, v17
	ds_write2_b32 v16, v8, v0 offset1:16
	ds_write2_b32 v16, v9, v1 offset0:64 offset1:80
	ds_write2_b32 v16, v10, v2 offset0:128 offset1:144
	ds_write2_b32 v16, v11, v3 offset0:192 offset1:208
	s_nop 0
	ds_write2_b32 v16, v4, v12 offset0:32 offset1:48
	ds_write2_b32 v16, v5, v13 offset0:96 offset1:112
	ds_write2_b32 v16, v6, v14 offset0:160 offset1:176
	ds_write2_b32 v16, v7, v15 offset0:224 offset1:240
	v_lshl_add_u32 v0, v146, 2, 0
	s_waitcnt lgkmcnt(0)
	s_barrier
; DI void compress_item(const Args& a, int l, int item, unsigned char* lds, int tid) {
;     ...
;     { float s0 = 0.f, s1 = 0.f;
; #pragma unroll
;       for (int w = 0; w < 8; ++w) { s0 += part[w * 1024 + tid]; s1 += part[w * 1024 + 512 + tid]; }
;       hs[tid] = s0; hs[512 + tid] = s1; }
;     __syncthreads();
;     { const float b0 = hs[15 * 64 + (tid & 63)]; const float x0 = hs[tid] + b0, x1 = hs[512 + tid] + b0;
;       __syncthreads();
;       hs[tid] = x0 / (1.0f + __expf(-x0)); hs[512 + tid] = x1 / (1.0f + __expf(-x1)); }
;     __syncthreads();
;     { const int r0 = wave, r1 = wave + 8; float o0 = 0.f, o1 = 0.f;
; #pragma unroll
;       for (int k16 = 0; k16 < 4; ++k16) { float wv[16];
; #pragma unroll
;           for (int k = 0; k < 16; ++k) wv[k] = w2[(k16 * 16 + k) * 64 + lane];
; #pragma unroll
;           for (int k = 0; k < 16; ++k) { o0 += hs[r0 * 64 + k16 * 16 + k] * wv[k]; o1 += hs[r1 * 64 + k16 * 16 + k] * wv[k]; } }
	ds_read2st64_b32 v[2:3], v0 offset1:8
	s_waitcnt lgkmcnt(0)
	v_add_f32_e32 v1, 0, v2
	v_add_f32_e32 v4, 0, v3
	ds_read2st64_b32 v[2:3], v0 offset0:16 offset1:24
	s_waitcnt lgkmcnt(0)
	v_add_f32_e32 v1, v1, v2
	v_add_f32_e32 v4, v4, v3
	ds_read2st64_b32 v[2:3], v0 offset0:32 offset1:40
	s_waitcnt lgkmcnt(0)
	v_add_f32_e32 v1, v1, v2
	v_add_f32_e32 v4, v4, v3
	ds_read2st64_b32 v[2:3], v0 offset0:48 offset1:56
	s_waitcnt lgkmcnt(0)
	v_add_f32_e32 v1, v1, v2
	v_add_f32_e32 v4, v4, v3
	ds_read2st64_b32 v[2:3], v0 offset0:64 offset1:72
	s_waitcnt lgkmcnt(0)
	v_add_f32_e32 v1, v1, v2
	v_add_f32_e32 v4, v4, v3
	ds_read2st64_b32 v[2:3], v0 offset0:80 offset1:88
	s_waitcnt lgkmcnt(0)
	v_add_f32_e32 v1, v1, v2
	v_add_f32_e32 v4, v4, v3
	ds_read2st64_b32 v[2:3], v0 offset0:96 offset1:104
	s_waitcnt lgkmcnt(0)
	v_add_f32_e32 v1, v1, v2
	v_add_f32_e32 v4, v4, v3
	ds_read2st64_b32 v[2:3], v0 offset0:112 offset1:120
	s_waitcnt lgkmcnt(0)
	v_add_f32_e32 v1, v1, v2
	v_add_f32_e32 v2, v4, v3
	ds_write2st64_b32 v0, v1, v2 offset0:128 offset1:136
	v_add_u32_e32 v1, 0, v160
	s_waitcnt lgkmcnt(0)
	s_barrier
	ds_read_b32 v1, v1 offset:36608
	ds_read2st64_b32 v[2:3], v0 offset0:128 offset1:136
	s_waitcnt lgkmcnt(0)
	s_barrier
	v_add_f32_e32 v2, v1, v2
	v_add_f32_e32 v1, v1, v3
	v_mul_f32_e32 v3, 0xbfb8aa3b, v2
	v_exp_f32_e32 v3, v3
	s_nop 0
	v_add_f32_e32 v3, 1.0, v3
	v_div_scale_f32 v4, s[6:7], v3, v3, v2
	v_rcp_f32_e32 v5, v4
	s_nop 0
	v_fma_f32 v6, -v4, v5, 1.0
	v_fmac_f32_e32 v5, v6, v5
	v_div_scale_f32 v6, vcc, v2, v3, v2
	v_mul_f32_e32 v7, v6, v5
	v_fma_f32 v8, -v4, v7, v6
	v_fmac_f32_e32 v7, v8, v5
	v_fma_f32 v4, -v4, v7, v6
	v_div_fmas_f32 v4, v4, v5, v7
	v_div_fixup_f32 v2, v4, v3, v2
	v_mul_f32_e32 v3, 0xbfb8aa3b, v1
	v_exp_f32_e32 v3, v3
	s_nop 0
	v_add_f32_e32 v3, 1.0, v3
	v_div_scale_f32 v4, s[6:7], v3, v3, v1
	v_rcp_f32_e32 v5, v4
	s_and_b32 s7, s59, 0x3fffffc0
	s_lshl_b32 s7, s7, 2
	s_add_i32 s7, s7, 0
	v_fma_f32 v6, -v4, v5, 1.0
	v_fmac_f32_e32 v5, v6, v5
	v_div_scale_f32 v6, vcc, v1, v3, v1
	v_mul_f32_e32 v7, v6, v5
	v_fma_f32 v8, -v4, v7, v6
	v_fmac_f32_e32 v7, v8, v5
	v_fma_f32 v4, -v4, v7, v6
	v_div_fmas_f32 v4, v4, v5, v7
	v_div_fixup_f32 v1, v4, v3, v1
	ds_write2st64_b32 v0, v2, v1 offset0:128 offset1:136
	s_waitcnt lgkmcnt(0)
	s_barrier
	global_load_dword v4, v160, s[0:1]
	global_load_dword v23, v160, s[0:1] offset:256
	global_load_dword v40, v160, s[0:1] offset:512
	global_load_dword v41, v160, s[0:1] offset:768
	global_load_dword v42, v160, s[0:1] offset:1024
	global_load_dword v43, v160, s[0:1] offset:1280
	global_load_dword v44, v160, s[0:1] offset:1536
	global_load_dword v45, v160, s[0:1] offset:1792
	global_load_dword v46, v160, s[0:1] offset:2048
	global_load_dword v47, v160, s[0:1] offset:2304
	global_load_dword v48, v160, s[0:1] offset:2560
	global_load_dword v49, v160, s[0:1] offset:2816
	global_load_dword v50, v160, s[0:1] offset:3072
	global_load_dword v51, v160, s[0:1] offset:3328
	global_load_dword v52, v160, s[0:1] offset:3584
	global_load_dword v53, v160, s[0:1] offset:3840
	v_mov_b32_e32 v3, s7
	ds_read_b128 v[6:9], v3 offset:32768
	ds_read_b128 v[10:13], v3 offset:32784
	ds_read_b128 v[14:17], v3 offset:32800
	ds_read_b128 v[18:21], v3 offset:32816
	s_add_i32 s6, s8, 8
	s_lshl_b32 s10, s6, 8
	s_add_i32 s10, s10, 0
	v_mov_b32_e32 v2, s10
	ds_read_b128 v[24:27], v2 offset:32768
	ds_read_b128 v[28:31], v2 offset:32784
	ds_read_b128 v[32:35], v2 offset:32800
	ds_read_b128 v[36:39], v2 offset:32816
	v_lshl_add_u64 v[0:1], s[0:1], 0, v[160:161]
	s_movk_i32 s0, 0x3000
	s_cmp_lg_u32 s9, 0
	s_waitcnt vmcnt(15) lgkmcnt(7)
	v_fma_f32 v5, v4, v6, 0
	s_waitcnt vmcnt(14)
	v_fmac_f32_e32 v5, v23, v7
	s_waitcnt vmcnt(13)
	v_fmac_f32_e32 v5, v40, v8
	s_waitcnt vmcnt(12)
	v_fmac_f32_e32 v5, v41, v9
	s_waitcnt vmcnt(11) lgkmcnt(6)
	v_fmac_f32_e32 v5, v42, v10
	s_waitcnt vmcnt(10)
	v_fmac_f32_e32 v5, v43, v11
	s_waitcnt vmcnt(9)
	v_fmac_f32_e32 v5, v44, v12
	s_waitcnt lgkmcnt(3)
	v_fma_f32 v4, v4, v24, 0
	s_waitcnt vmcnt(8)
	v_fmac_f32_e32 v5, v45, v13
	v_fmac_f32_e32 v4, v23, v25
	s_waitcnt vmcnt(7)
	v_fmac_f32_e32 v5, v46, v14
	v_fmac_f32_e32 v4, v40, v26
	s_waitcnt vmcnt(6)
	v_fmac_f32_e32 v5, v47, v15
	v_fmac_f32_e32 v4, v41, v27
	s_waitcnt vmcnt(5)
	v_fmac_f32_e32 v5, v48, v16
	s_waitcnt lgkmcnt(2)
	v_fmac_f32_e32 v4, v42, v28
	s_waitcnt vmcnt(4)
	v_fmac_f32_e32 v5, v49, v17
	v_add_co_u32_e32 v6, vcc, s85, v0
	v_fmac_f32_e32 v4, v43, v29
	s_waitcnt vmcnt(3)
	v_fmac_f32_e32 v5, v50, v18
	v_addc_co_u32_e32 v7, vcc, 0, v1, vcc
	v_fmac_f32_e32 v4, v44, v30
	s_waitcnt vmcnt(2)
	v_fmac_f32_e32 v5, v51, v19
	v_add_co_u32_e32 v14, vcc, s89, v0
	v_fmac_f32_e32 v4, v45, v31
	s_waitcnt vmcnt(1)
	v_fmac_f32_e32 v5, v52, v20
	v_addc_co_u32_e32 v15, vcc, 0, v1, vcc
	s_waitcnt lgkmcnt(1)
	v_fmac_f32_e32 v4, v46, v32
	s_waitcnt vmcnt(0)
	v_fmac_f32_e32 v5, v53, v21
	global_load_dword v16, v[14:15], off offset:-4096
	global_load_dword v17, v[6:7], off offset:256
	global_load_dword v18, v[6:7], off offset:512
	global_load_dword v19, v[6:7], off offset:768
	global_load_dword v20, v[6:7], off offset:1024
	global_load_dword v21, v[6:7], off offset:1280
	global_load_dword v23, v[6:7], off offset:1536
	global_load_dword v24, v[6:7], off offset:1792
	global_load_dword v25, v[6:7], off offset:2048
	global_load_dword v26, v[6:7], off offset:2304
	global_load_dword v27, v[6:7], off offset:2560
	global_load_dword v28, v[6:7], off offset:2816
	global_load_dword v29, v[6:7], off offset:3072
	global_load_dword v30, v[6:7], off offset:3328
	global_load_dword v31, v[6:7], off offset:3584
	global_load_dword v32, v[6:7], off offset:3840
	v_fmac_f32_e32 v4, v47, v33
	v_fmac_f32_e32 v4, v48, v34
	v_fmac_f32_e32 v4, v49, v35
	ds_read_b128 v[6:9], v3 offset:32832
	ds_read_b128 v[10:13], v2 offset:32832
	s_waitcnt lgkmcnt(2)
; DI void compress_item(const Args& a, int l, int item, unsigned char* lds, int tid) {
;     ...
;     { const int r0 = wave, r1 = wave + 8; float o0 = 0.f, o1 = 0.f;
; #pragma unroll
;       for (int k16 = 0; k16 < 4; ++k16) { float wv[16];
; #pragma unroll
;           for (int k = 0; k < 16; ++k) wv[k] = w2[(k16 * 16 + k) * 64 + lane];
; #pragma unroll
;           for (int k = 0; k < 16; ++k) { o0 += hs[r0 * 64 + k16 * 16 + k] * wv[k]; o1 += hs[r1 * 64 + k16 * 16 + k] * wv[k]; } }
	v_fmac_f32_e32 v4, v50, v36
	v_fmac_f32_e32 v4, v51, v37
	v_fmac_f32_e32 v4, v52, v38
	v_fmac_f32_e32 v4, v53, v39
	s_waitcnt vmcnt(15) lgkmcnt(1)
	v_fmac_f32_e32 v5, v16, v6
	s_waitcnt lgkmcnt(0)
	v_fmac_f32_e32 v4, v16, v10
	s_waitcnt vmcnt(14)
	v_fmac_f32_e32 v5, v17, v7
	v_fmac_f32_e32 v4, v17, v11
	s_waitcnt vmcnt(13)
	v_fmac_f32_e32 v5, v18, v8
	v_fmac_f32_e32 v4, v18, v12
	s_waitcnt vmcnt(12)
	v_fmac_f32_e32 v5, v19, v9
	v_fmac_f32_e32 v4, v19, v13
	ds_read_b128 v[6:9], v3 offset:32848
	ds_read_b128 v[10:13], v2 offset:32848
	s_waitcnt vmcnt(11) lgkmcnt(1)
	v_fmac_f32_e32 v5, v20, v6
	s_waitcnt lgkmcnt(0)
	v_fmac_f32_e32 v4, v20, v10
	s_waitcnt vmcnt(10)
	v_fmac_f32_e32 v5, v21, v7
	v_fmac_f32_e32 v4, v21, v11
	s_waitcnt vmcnt(9)
	v_fmac_f32_e32 v5, v23, v8
	v_fmac_f32_e32 v4, v23, v12
	s_waitcnt vmcnt(8)
	v_fmac_f32_e32 v5, v24, v9
	v_fmac_f32_e32 v4, v24, v13
	ds_read_b128 v[6:9], v3 offset:32864
	ds_read_b128 v[10:13], v2 offset:32864
	s_waitcnt vmcnt(7) lgkmcnt(1)
	v_fmac_f32_e32 v5, v25, v6
	s_waitcnt lgkmcnt(0)
	v_fmac_f32_e32 v4, v25, v10
	s_waitcnt vmcnt(6)
	v_fmac_f32_e32 v5, v26, v7
	v_fmac_f32_e32 v4, v26, v11
	s_waitcnt vmcnt(5)
	v_fmac_f32_e32 v5, v27, v8
	v_fmac_f32_e32 v4, v27, v12
	s_waitcnt vmcnt(4)
	v_fmac_f32_e32 v5, v28, v9
	v_fmac_f32_e32 v4, v28, v13
	ds_read_b128 v[6:9], v3 offset:32880
	ds_read_b128 v[10:13], v2 offset:32880
	s_waitcnt vmcnt(3) lgkmcnt(1)
	v_fmac_f32_e32 v5, v29, v6
	s_waitcnt lgkmcnt(0)
	v_fmac_f32_e32 v4, v29, v10
	s_waitcnt vmcnt(2)
	v_fmac_f32_e32 v5, v30, v7
	v_fmac_f32_e32 v4, v30, v11
	s_waitcnt vmcnt(1)
	v_fmac_f32_e32 v5, v31, v8
	v_fmac_f32_e32 v4, v31, v12
	global_load_dword v16, v[14:15], off
	global_load_dword v17, v[14:15], off offset:256
	global_load_dword v18, v[14:15], off offset:512
	global_load_dword v19, v[14:15], off offset:768
	global_load_dword v20, v[14:15], off offset:1024
	global_load_dword v21, v[14:15], off offset:1280
	global_load_dword v23, v[14:15], off offset:1536
	global_load_dword v24, v[14:15], off offset:1792
	global_load_dword v25, v[14:15], off offset:2048
	global_load_dword v26, v[14:15], off offset:2304
	global_load_dword v27, v[14:15], off offset:2560
	global_load_dword v28, v[14:15], off offset:2816
	global_load_dword v29, v[14:15], off offset:3072
	global_load_dword v30, v[14:15], off offset:3328
	global_load_dword v31, v[14:15], off offset:3584
	s_nop 0
	global_load_dword v14, v[14:15], off offset:3840
	s_waitcnt vmcnt(16)
	v_fmac_f32_e32 v5, v32, v9
	v_fmac_f32_e32 v4, v32, v13
	ds_read_b128 v[6:9], v3 offset:32896
	ds_read_b128 v[10:13], v2 offset:32896
	s_waitcnt vmcnt(15) lgkmcnt(1)
	v_fmac_f32_e32 v5, v16, v6
	s_waitcnt lgkmcnt(0)
	v_fmac_f32_e32 v4, v16, v10
	s_waitcnt vmcnt(14)
	v_fmac_f32_e32 v5, v17, v7
	v_fmac_f32_e32 v4, v17, v11
	s_waitcnt vmcnt(13)
	v_fmac_f32_e32 v5, v18, v8
	v_fmac_f32_e32 v4, v18, v12
	s_waitcnt vmcnt(12)
	v_fmac_f32_e32 v5, v19, v9
	v_fmac_f32_e32 v4, v19, v13
	ds_read_b128 v[6:9], v3 offset:32912
	ds_read_b128 v[10:13], v2 offset:32912
	s_waitcnt vmcnt(11) lgkmcnt(1)
	v_fmac_f32_e32 v5, v20, v6
	s_waitcnt lgkmcnt(0)
	v_fmac_f32_e32 v4, v20, v10
	s_waitcnt vmcnt(10)
	v_fmac_f32_e32 v5, v21, v7
	v_fmac_f32_e32 v4, v21, v11
	s_waitcnt vmcnt(9)
	v_fmac_f32_e32 v5, v23, v8
	v_fmac_f32_e32 v4, v23, v12
	s_waitcnt vmcnt(8)
	v_fmac_f32_e32 v5, v24, v9
	v_fmac_f32_e32 v4, v24, v13
	ds_read_b128 v[6:9], v3 offset:32928
	ds_read_b128 v[10:13], v2 offset:32928
	v_add_co_u32_e32 v20, vcc, s0, v0
	s_mov_b64 s[0:1], -1
	s_waitcnt vmcnt(7) lgkmcnt(1)
	v_fmac_f32_e32 v5, v25, v6
	s_waitcnt lgkmcnt(0)
	v_fmac_f32_e32 v4, v25, v10
	s_waitcnt vmcnt(6)
	v_fmac_f32_e32 v5, v26, v7
	v_fmac_f32_e32 v4, v26, v11
	s_waitcnt vmcnt(5)
	v_fmac_f32_e32 v5, v27, v8
	v_fmac_f32_e32 v4, v27, v12
	s_waitcnt vmcnt(4)
	v_fmac_f32_e32 v5, v28, v9
	v_fmac_f32_e32 v4, v28, v13
	ds_read_b128 v[6:9], v3 offset:32944
	ds_read_b128 v[10:13], v2 offset:32944
	v_addc_co_u32_e32 v21, vcc, 0, v1, vcc
	s_waitcnt vmcnt(3) lgkmcnt(1)
	v_fmac_f32_e32 v5, v29, v6
	s_waitcnt lgkmcnt(0)
	v_fmac_f32_e32 v4, v29, v10
	s_waitcnt vmcnt(2)
	v_fmac_f32_e32 v5, v30, v7
	v_fmac_f32_e32 v4, v30, v11
	s_waitcnt vmcnt(1)
	v_fmac_f32_e32 v5, v31, v8
	v_fmac_f32_e32 v4, v31, v12
	s_waitcnt vmcnt(0)
	v_fmac_f32_e32 v5, v14, v9
	v_fmac_f32_e32 v4, v14, v13
	global_load_dword v16, v[20:21], off
	global_load_dword v15, v[20:21], off offset:256
	global_load_dword v14, v[20:21], off offset:512
	global_load_dword v13, v[20:21], off offset:768
	global_load_dword v8, v[20:21], off offset:1024
	global_load_dword v7, v[20:21], off offset:1280
	global_load_dword v6, v[20:21], off offset:1536
	global_load_dword v1, v[20:21], off offset:1792
	global_load_dword v0, v[20:21], off offset:2048
	global_load_dword v17, v[20:21], off offset:2304
	global_load_dword v18, v[20:21], off offset:2560
	global_load_dword v19, v[20:21], off offset:2816
	global_load_dword v12, v[20:21], off offset:3072
	global_load_dword v11, v[20:21], off offset:3328
	global_load_dword v10, v[20:21], off offset:3584
	global_load_dword v9, v[20:21], off offset:3840
	ds_read_b128 v[24:27], v3 offset:32960
	ds_read_b128 v[28:31], v2 offset:32960
	s_waitcnt vmcnt(15) lgkmcnt(1)
	v_fmac_f32_e32 v5, v16, v24
	s_waitcnt lgkmcnt(0)
	v_fmac_f32_e32 v4, v16, v28
	s_waitcnt vmcnt(14)
	v_fmac_f32_e32 v5, v15, v25
	v_fmac_f32_e32 v4, v15, v29
	s_waitcnt vmcnt(13)
	v_fmac_f32_e32 v5, v14, v26
	v_fmac_f32_e32 v4, v14, v30
	s_waitcnt vmcnt(12)
	v_fmac_f32_e32 v5, v13, v27
	v_fmac_f32_e32 v4, v13, v31
	ds_read_b128 v[24:27], v3 offset:32976
	ds_read_b128 v[28:31], v2 offset:32976
	s_waitcnt vmcnt(11) lgkmcnt(1)
	v_fmac_f32_e32 v5, v8, v24
	s_waitcnt lgkmcnt(0)
	v_fmac_f32_e32 v4, v8, v28
	s_waitcnt vmcnt(10)
	v_fmac_f32_e32 v5, v7, v25
	v_fmac_f32_e32 v4, v7, v29
	s_waitcnt vmcnt(9)
	v_fmac_f32_e32 v5, v6, v26
	v_fmac_f32_e32 v4, v6, v30
	s_waitcnt vmcnt(8)
	v_fmac_f32_e32 v5, v1, v27
	v_fmac_f32_e32 v4, v1, v31
	ds_read_b128 v[24:27], v3 offset:32992
	ds_read_b128 v[28:31], v2 offset:32992
	s_waitcnt vmcnt(7) lgkmcnt(1)
	v_fmac_f32_e32 v5, v0, v24
	s_waitcnt lgkmcnt(0)
	v_fmac_f32_e32 v4, v0, v28
	s_waitcnt vmcnt(6)
	v_fmac_f32_e32 v5, v17, v25
	v_fmac_f32_e32 v4, v17, v29
	ds_read_b128 v[14:17], v3 offset:33008
	ds_read_b128 v[0:3], v2 offset:33008
	s_waitcnt vmcnt(5)
	v_fmac_f32_e32 v5, v18, v26
	v_fmac_f32_e32 v4, v18, v30
	s_waitcnt vmcnt(4)
	v_fmac_f32_e32 v5, v19, v27
	v_fmac_f32_e32 v4, v19, v31
	s_waitcnt vmcnt(3) lgkmcnt(1)
	v_fmac_f32_e32 v5, v12, v14
	s_waitcnt lgkmcnt(0)
	v_fmac_f32_e32 v4, v12, v0
	s_waitcnt vmcnt(2)
	v_fmac_f32_e32 v5, v11, v15
	v_fmac_f32_e32 v4, v11, v1
	s_waitcnt vmcnt(1)
	v_fmac_f32_e32 v5, v10, v16
	v_fmac_f32_e32 v4, v10, v2
	s_waitcnt vmcnt(0)
	v_fmac_f32_e32 v5, v9, v17
	v_fmac_f32_e32 v4, v9, v3
	s_cbranch_scc0 .LBB0_343
; DI bf16_t f2bf(float f) { return (bf16_t)(cvtpk(f, 0.f) & 0xffffu); }
; DI void compress_item(const Args& a, int l, int item, unsigned char* lds, int tid) {
;     ...
;           VCT[(((size_t)b * 2 + g) * 64 + lane) * 256 + 15 * tix + r0] = f2bf(o0);
;           if (r1 < 15) VCT[(((size_t)b * 2 + g) * 64 + lane) * 256 + 15 * tix + r1] = f2bf(o1);
	s_lshl_b32 s0, s52, 6
	s_lshl_b32 s1, s53, 7
	v_cvt_pk_bf16_f32 v6, v5, s0
	s_or_b32 s0, s1, s0
	v_or_b32_e32 v0, s0, v22
	v_readlane_b32 s0, v254, 48
	v_lshlrev_b32_e32 v0, 9, v0
	v_mov_b32_e32 v1, v161
	v_readlane_b32 s1, v254, 49
	s_lshl_b32 s80, s54, 1
	s_ashr_i32 s9, s8, 31
	v_lshl_add_u64 v[0:1], s[0:1], 0, v[0:1]
	v_lshl_add_u64 v[2:3], v[0:1], 0, s[80:81]
	v_lshl_add_u64 v[2:3], s[8:9], 1, v[2:3]
	s_cmp_gt_i32 s8, 6
	global_store_short v[2:3], v6, off
	s_cbranch_scc1 .LBB0_340
	v_cvt_pk_bf16_f32 v6, v4, s0
	global_store_short v[2:3], v6, off offset:16
